# GQA loop back edge rotated: loop-carried copies moved in front of the closing barrier, single taken branch after it (asm guide 7.11); on top of v42
# baseline (speedup 1.0000x reference)
; #define SWRITE(b, i) do { *(bf16x8*)((char*)V_lds + (b) * SHM_V + vst0) = sr_[i].vs0;          \
;     *(bf16x8*)((char*)V_lds + (b) * SHM_V + vst1) = sr_[i].vs1; int kc = sc * 2;               \
;     *(bf16x8*)((char*)K_lds + (b) * SHM_K + KSWZ(sr, kc)) = sr_[i].ks0;                       \
;     *(bf16x8*)((char*)K_lds + (b) * SHM_K + KSWZ(32 + sr, kc)) = sr_[i].ks1; } while (0)
; #define SWAIT() asm volatile("s_waitcnt vmcnt(4)" ::: "memory")
; #define RESC(a) do { if (__any((a) < 1.f)) { if (hi == 0) al_l[r32] = (a); asm volatile("s_waitcnt lgkmcnt(0)" ::: "memory"); \
;     _Pragma("unroll") for (int d = 0; d < 4; ++d) _Pragma("unroll") for (int r = 0; r < 16; ++r) o[d][r] *= al_l[crow(r, hi)]; } } while (0)
; #define SWRITE(b, i) do { *(i32x4*)(K_lds + (b) * F8_KB + kst) = sr_[i].ks; *(i32x4*)(V_lds + (b) * F8_KB + vst) = sr_[i].vs; } while (0)
; #define SWAIT() asm volatile("s_waitcnt vmcnt(2)" ::: "memory")
; #define RESC(a) do { if (__any((a) < 1.f)) { if (hi == 0) al_l[r32] = (a); asm volatile("s_waitcnt lgkmcnt(0)" ::: "memory"); \
;     _Pragma("unroll") for (int d = 0; d < 4; ++d) _Pragma("unroll") for (int r = 0; r < 16; ++r) o[d][r] *= al_l[crow(r, hi)]; } } while (0)
; template <int LDQ, int LDK, int LDO, int OSH>
; __device__ __forceinline__ void attn_body_f8(const unsigned char* Qb, const unsigned char* __restrict__ Kh, const unsigned char* __restrict__ VTh, long ldv, unsigned char* Ob, int seq, char* lds) {
;     ...
;     __syncthreads(); SWAIT(); SWRITE(1, SO);
;     RESC(alA); __syncthreads();
;   }
.LBB0_381:
	v_mov_b32_e32 v234, v188
	v_mov_b32_e32 v208, v179
	s_and_b64 vcc, exec, s[8:9]
	s_waitcnt lgkmcnt(0)
	s_barrier
	s_cbranch_vccz .LBB0_366
	s_branch .LBB0_385
